# band epilogue z loads requested at epilogue top; diff head-table copy with all strided dwords in flight at once
# speedup vs baseline: 1.0049x; 1.0049x over previous
; DI void band_item(const Params& P, char* lds_blk, int layer, int bp) {
;     ...
;     const int ch = lane & 7;
; #pragma unroll
;     for (int j = 0; j < 4; ++j) {
;         const int rl = (lane >> 3) + 8 * j;
;         const f32x4 a = *(const f32x4*)(sO + rl * OP + ch * 32), b = *(const f32x4*)(sO + rl * OP + ch * 32 + 16);
;         const size_t orow = base_row + (size_t)(32 * w + rl) * dil;
;         if (type == 0) {
;             const u32x4 zz = *(const u32x4*)(Ph + orow * PO + OFF_Z + head * 64 + ch * 8);
.LBB0_222:
	s_and_b64 vcc, exec, s[40:41]
	s_cbranch_vccnz .Lz_early_skip
	v_lshrrev_b32_e32 v58, 3, v107
	v_or_b32_e32 v58, v111, v58
	v_lshlrev_b32_e32 v58, s50, v58
	v_add_u32_e32 v58, s51, v58
	v_mov_b64_e32 v[60:61], s[34:35]
	v_mad_u64_u32 v[60:61], vcc, v58, s52, v[60:61]
	v_mov_b32_e32 v62, v106
	v_ashrrev_i32_e32 v63, 31, v106
	v_lshl_add_u64 v[60:61], v[62:63], 1, v[60:61]
	v_lshlrev_b32_e32 v62, 1, v110
	v_mov_b32_e32 v63, v1
	v_lshl_add_u64 v[60:61], v[60:61], 0, v[62:63]
	v_add_co_u32_e32 v60, vcc, 0x2000, v60
	s_nop 1
	v_addc_co_u32_e32 v61, vcc, 0, v61, vcc
	global_load_dwordx4 v[238:241], v[60:61], off offset:1792
	s_lshl_b32 s22, s52, 3
	s_lshl_b32 s22, s22, s50
	s_mov_b32 s23, 0
	v_lshl_add_u64 v[60:61], v[60:61], 0, s[22:23]
	global_load_dwordx4 v[242:245], v[60:61], off offset:1792
	v_lshl_add_u64 v[60:61], v[60:61], 0, s[22:23]
	global_load_dwordx4 v[246:249], v[60:61], off offset:1792
	v_lshl_add_u64 v[60:61], v[60:61], 0, s[22:23]
	global_load_dwordx4 v[250:253], v[60:61], off offset:1792

; DI unsigned pk2(float lo, float hi) { fl2_t f = {lo, hi}; bf2_t b = __builtin_convertvector(f, bf2_t); return __builtin_bit_cast(unsigned, b); }
; DI float bflo(unsigned u) { return __uint_as_float(u << 16); }
; DI float bfhi(unsigned u) { return __uint_as_float(u & 0xffff0000u); }
; DI float silu_f(float z) { return z / (1.f + __expf(-z)); }
; DI void band_item(const Params& P, char* lds_blk, int layer, int bp) {
;     ...
;         if (type == 0) {
;             const u32x4 zz = *(const u32x4*)(Ph + orow * PO + OFF_Z + head * 64 + ch * 8);
;             u32x4 o = {pk2(a.x * silu_f(bflo(zz.x)), a.y * silu_f(bfhi(zz.x))), pk2(a.z * silu_f(bflo(zz.y)), a.w * silu_f(bfhi(zz.y))),
;                        pk2(b.x * silu_f(bflo(zz.z)), b.y * silu_f(bfhi(zz.z))), pk2(b.z * silu_f(bflo(zz.w)), b.w * silu_f(bfhi(zz.w)))};
;             *(u32x4*)(Ph + orow * PO + OFF_AQ + head * 64 + ch * 8) = o;
.LBB0_228:
	v_ashrrev_i32_e32 v107, 31, v106
	s_andn2_b64 vcc, exec, s[0:1]
	v_lshlrev_b32_e32 v14, 1, v110
	s_cbranch_vccnz .LBB0_230
	v_mov_b64_e32 v[6:7], s[34:35]
	v_mad_u64_u32 v[18:19], s[0:1], v0, s52, v[6:7]
	v_lshl_add_u64 v[6:7], v[106:107], 1, v[18:19]
	v_mov_b32_e32 v15, v1
	v_lshl_add_u64 v[6:7], v[6:7], 0, v[14:15]
	v_add_co_u32_e32 v6, vcc, 0x2000, v6
	s_nop 1
	v_addc_co_u32_e32 v7, vcc, 0, v7, vcc
	s_waitcnt vmcnt(0) lgkmcnt(0)
	v_mov_b32_e32 v6, v238
	v_mov_b32_e32 v7, v239
	v_mov_b32_e32 v8, v240
	v_mov_b32_e32 v9, v241
	v_lshlrev_b32_e32 v0, 16, v6
	v_and_b32_e32 v6, 0xffff0000, v6
	v_mul_f32_e32 v15, 0xbfb8aa3b, v0
	v_exp_f32_e32 v22, v15
	v_mul_f32_e32 v15, 0xbfb8aa3b, v6
	v_exp_f32_e32 v23, v15
	s_nop 0
	v_pk_add_f32 v[22:23], v[22:23], 1.0 op_sel_hi:[1,0]
	s_nop 0
	v_div_scale_f32 v15, s[0:1], v23, v23, v6
	v_rcp_f32_e32 v24, v15
	s_nop 0
	v_fma_f32 v25, -v15, v24, 1.0
	v_fmac_f32_e32 v24, v25, v24
	v_div_scale_f32 v25, vcc, v6, v23, v6
	v_mul_f32_e32 v26, v25, v24
	v_fma_f32 v27, -v15, v26, v25
	v_fmac_f32_e32 v26, v27, v24
	v_fma_f32 v15, -v15, v26, v25
	v_div_fmas_f32 v15, v15, v24, v26
	v_div_fixup_f32 v23, v15, v23, v6
	v_div_scale_f32 v6, s[0:1], v22, v22, v0
	v_rcp_f32_e32 v15, v6
	s_nop 0
	v_fma_f32 v24, -v6, v15, 1.0
	v_fmac_f32_e32 v15, v24, v15
	v_div_scale_f32 v24, vcc, v0, v22, v0
	v_mul_f32_e32 v25, v24, v15
	v_fma_f32 v26, -v6, v25, v24
	v_fmac_f32_e32 v25, v26, v15
	v_fma_f32 v6, -v6, v25, v24
	v_div_fmas_f32 v6, v6, v15, v25
	v_div_fixup_f32 v22, v6, v22, v0
	v_pk_mul_f32 v[10:11], v[10:11], v[22:23]
	v_lshlrev_b32_e32 v0, 16, v7
	v_and_b32_e32 v7, 0xffff0000, v7
	v_cvt_pk_bf16_f32 v6, v10, v11
	v_mul_f32_e32 v10, 0xbfb8aa3b, v0
	v_mul_f32_e32 v11, 0xbfb8aa3b, v7
	v_exp_f32_e32 v10, v10
	v_exp_f32_e32 v11, v11
	s_nop 0
	v_pk_add_f32 v[10:11], v[10:11], 1.0 op_sel_hi:[1,0]
	s_nop 0
	v_div_scale_f32 v15, s[0:1], v11, v11, v7
	v_rcp_f32_e32 v22, v15
	s_nop 0
	v_fma_f32 v23, -v15, v22, 1.0
	v_fmac_f32_e32 v22, v23, v22
	v_div_scale_f32 v23, vcc, v7, v11, v7
	v_mul_f32_e32 v24, v23, v22
	v_fma_f32 v25, -v15, v24, v23
	v_fmac_f32_e32 v24, v25, v22
	v_fma_f32 v15, -v15, v24, v23
	v_div_fmas_f32 v15, v15, v22, v24
	v_div_fixup_f32 v11, v15, v11, v7
	v_div_scale_f32 v7, s[0:1], v10, v10, v0
	v_rcp_f32_e32 v15, v7
	s_nop 0
	v_fma_f32 v22, -v7, v15, 1.0
	v_fmac_f32_e32 v15, v22, v15
	v_div_scale_f32 v22, vcc, v0, v10, v0
	v_mul_f32_e32 v23, v22, v15
	v_fma_f32 v24, -v7, v23, v22
	v_fmac_f32_e32 v23, v24, v15
	v_fma_f32 v7, -v7, v23, v22
	v_div_fmas_f32 v7, v7, v15, v23
	v_div_fixup_f32 v10, v7, v10, v0
	v_pk_mul_f32 v[10:11], v[12:13], v[10:11]
	v_lshlrev_b32_e32 v0, 16, v8
	v_and_b32_e32 v8, 0xffff0000, v8
	v_cvt_pk_bf16_f32 v7, v10, v11
	v_mul_f32_e32 v10, 0xbfb8aa3b, v0
	v_mul_f32_e32 v11, 0xbfb8aa3b, v8
	v_exp_f32_e32 v10, v10
	v_exp_f32_e32 v11, v11
	s_nop 0
	v_pk_add_f32 v[10:11], v[10:11], 1.0 op_sel_hi:[1,0]
	s_nop 0
	v_div_scale_f32 v12, s[0:1], v11, v11, v8
	v_rcp_f32_e32 v13, v12
	s_nop 0
	v_fma_f32 v15, -v12, v13, 1.0
	v_fmac_f32_e32 v13, v15, v13
	v_div_scale_f32 v15, vcc, v8, v11, v8
	v_mul_f32_e32 v22, v15, v13
	v_fma_f32 v23, -v12, v22, v15
	v_fmac_f32_e32 v22, v23, v13
	v_fma_f32 v12, -v12, v22, v15
	v_div_fmas_f32 v12, v12, v13, v22
	v_div_fixup_f32 v11, v12, v11, v8
	v_div_scale_f32 v8, s[0:1], v10, v10, v0
	v_rcp_f32_e32 v12, v8
	s_nop 0
	v_fma_f32 v13, -v8, v12, 1.0
	v_fmac_f32_e32 v12, v13, v12
	v_div_scale_f32 v13, vcc, v0, v10, v0
	v_mul_f32_e32 v15, v13, v12
	v_fma_f32 v22, -v8, v15, v13
	v_fmac_f32_e32 v15, v22, v12
	v_fma_f32 v8, -v8, v15, v13
	v_div_fmas_f32 v8, v8, v12, v15
	v_div_fixup_f32 v10, v8, v10, v0
	v_pk_mul_f32 v[2:3], v[2:3], v[10:11]
	v_lshlrev_b32_e32 v0, 16, v9
	v_and_b32_e32 v9, 0xffff0000, v9
	v_cvt_pk_bf16_f32 v8, v2, v3
	v_mul_f32_e32 v2, 0xbfb8aa3b, v0
	v_mul_f32_e32 v3, 0xbfb8aa3b, v9
	v_exp_f32_e32 v2, v2
	v_exp_f32_e32 v3, v3
	s_nop 0
	v_pk_add_f32 v[2:3], v[2:3], 1.0 op_sel_hi:[1,0]
	s_nop 0
	v_div_scale_f32 v10, s[0:1], v3, v3, v9
	v_rcp_f32_e32 v11, v10
	s_nop 0
	v_fma_f32 v12, -v10, v11, 1.0
	v_fmac_f32_e32 v11, v12, v11
	v_div_scale_f32 v12, vcc, v9, v3, v9
	v_mul_f32_e32 v13, v12, v11
	v_fma_f32 v15, -v10, v13, v12
	v_fmac_f32_e32 v13, v15, v11
	v_fma_f32 v10, -v10, v13, v12
	v_div_fmas_f32 v10, v10, v11, v13
	v_div_fixup_f32 v3, v10, v3, v9
	v_div_scale_f32 v9, s[0:1], v2, v2, v0
	v_rcp_f32_e32 v10, v9
	s_nop 0
	v_fma_f32 v11, -v9, v10, 1.0
	v_fmac_f32_e32 v10, v11, v10
	v_div_scale_f32 v11, vcc, v0, v2, v0
	v_mul_f32_e32 v12, v11, v10
	v_fma_f32 v13, -v9, v12, v11
	v_fmac_f32_e32 v12, v13, v10
	v_fma_f32 v9, -v9, v12, v11
	v_div_fmas_f32 v9, v9, v10, v12
	v_div_fixup_f32 v2, v9, v2, v0
	v_pk_mul_f32 v[2:3], v[4:5], v[2:3]
	s_nop 0
	v_cvt_pk_bf16_f32 v9, v2, v3

; DI void diff_item(const Params& P, char* lds, int layer, int pair, int qt, int& tab_head) {
;     ...
;     float* ctab = (float*)(lds + LDS_CTAB);
;     const float* tabg = (const float*)(P.ws + WS_TABC) + head * 2112;
;     if (tab_head != head) { for (int i = tid; i < 2112; i += NTHR) ctab[i] = tabg[i]; tab_head = head; }
;     const float cfar = tabg[2111];
.LBB0_243:
	s_and_b64 vcc, exec, s[0:1]
	s_cbranch_vccz .LBB0_198
	v_mov_b32_e32 v168, v174
	s_cmp_eq_u32 s49, s3
	s_movk_i32 s16, 0x83f
	s_cselect_b64 s[0:1], -1, 0
	v_cmp_lt_i32_e32 vcc, s16, v168
	s_or_b64 s[0:1], s[0:1], vcc
	v_lshlrev_b32_e32 v4, 2, v168
	s_and_saveexec_b64 s[22:23], s[0:1]
	s_xor_b64 s[0:1], exec, s[22:23]
	v_lshlrev_b32_e32 v4, 2, v168
	s_andn2_saveexec_b64 s[0:1], s[0:1]
	s_cbranch_execz .LBB0_250
	v_ashrrev_i32_e32 v169, 31, v168
	v_add_u32_e32 v0, 0xfffffe00, v168
	v_add_u32_e32 v5, s48, v4
	v_lshl_add_u64 v[2:3], v[168:169], 2, s[28:29]
	global_load_dword v6, v[2:3], off
	global_load_dword v7, v[2:3], off offset:2048
	s_mov_b64 s[40:41], 0x1000
	v_lshl_add_u64 v[8:9], v[2:3], 0, s[40:41]
	global_load_dword v12, v[8:9], off
	global_load_dword v13, v[8:9], off offset:2048
	v_cmp_gt_u32_e32 vcc, 64, v168
	s_and_saveexec_b64 s[22:23], vcc
	v_lshl_add_u64 v[8:9], v[8:9], 0, s[40:41]
	global_load_dword v14, v[8:9], off
	s_waitcnt vmcnt(0)
	ds_write_b32 v5, v14 offset:8192
	s_or_b64 exec, exec, s[22:23]
	s_waitcnt vmcnt(0)
	ds_write_b32 v5, v6
	ds_write_b32 v5, v7 offset:2048
	ds_write_b32 v5, v12 offset:4096
	ds_write_b32 v5, v13 offset:6144
